# v3 + attn_merge loop software-pipelined (6 loads of the next iteration in flight during compute)
# baseline (speedup 1.0000x reference)
; __device__ __forceinline__ float bflo(unsigned u) { return __uint_as_float(u << 16); }
; __device__ __forceinline__ float bfhi(unsigned u) { return __uint_as_float(u & 0xffff0000u); }
; __device__ __forceinline__ unsigned pk2(float lo, float hi) { f32x2 v = {lo, hi}; bf2_t b = __builtin_convertvector(v, bf2_t); return __builtin_bit_cast(unsigned, b); }
; __device__ __forceinline__ int opaque_tid(int wv) { int l; asm volatile("v_mbcnt_lo_u32_b32 %0, -1, 0\n\tv_mbcnt_hi_u32_b32 %0, -1, %0" : "=v"(l)); return (wv << 6) | l; }
; __device__ __forceinline__ void attn_merge(int wv, const Args& a) {
;     const int gt = blockIdx.x * NTHR + opaque_tid(wv), GT = NWG * NTHR;
;     const bf16_t* OG = (const bf16_t*)(a.ws + WS_AQ); const float* LSE = (const float*)(a.ws + WS_LSE); bf16_t* OB = (bf16_t*)(a.ws + WS_OB);
;     for (int i = gt; i < MTOK * 64; i += GT) {
;         const int tok = i >> 6, hh = (i >> 4) & 3, c = i & 15;
;         const float l0 = LSE[(size_t)tok * 12 + hh], l1 = LSE[(size_t)tok * 12 + 4 + hh], l2 = LSE[(size_t)tok * 12 + 8 + hh];
;         const float mxl = fmaxf(l0, fmaxf(l1, l2));
;         float a0 = __expf(l0 - mxl), a1 = __expf(l1 - mxl), a2 = __expf(l2 - mxl); const float inv = 1.f / (a0 + a1 + a2); a0 *= inv; a1 *= inv; a2 *= inv;
;         const u32x4 v0 = *(const u32x4*)(OG + (size_t)tok * ATW + hh * 128 + 8 * c), v1 = *(const u32x4*)(OG + (size_t)tok * ATW + (4 + hh) * 128 + 8 * c), v2 = *(const u32x4*)(OG + (size_t)tok * ATW + (8 + hh) * 128 + 8 * c);
;         u32x4 w;
;         w.x = pk2(a0 * bflo(v0.x) + a1 * bflo(v1.x) + a2 * bflo(v2.x), a0 * bfhi(v0.x) + a1 * bfhi(v1.x) + a2 * bfhi(v2.x));
;         w.y = pk2(a0 * bflo(v0.y) + a1 * bflo(v1.y) + a2 * bflo(v2.y), a0 * bfhi(v0.y) + a1 * bfhi(v1.y) + a2 * bfhi(v2.y));
;         w.z = pk2(a0 * bflo(v0.z) + a1 * bflo(v1.z) + a2 * bflo(v2.z), a0 * bfhi(v0.z) + a1 * bfhi(v1.z) + a2 * bfhi(v2.z));
;         w.w = pk2(a0 * bflo(v0.w) + a1 * bflo(v1.w) + a2 * bflo(v2.w), a0 * bfhi(v0.w) + a1 * bfhi(v1.w) + a2 * bfhi(v2.w));
;         *(u32x4*)(OB + (size_t)tok * 512 + hh * 128 + 8 * c) = w;
;     }
.LBB0_714:
	v_ashrrev_i32_e32 v14, 6, v0
	v_bfe_u32 v4, v0, 4, 2
	v_and_b32_e32 v15, 15, v0
	v_lshlrev_b32_e32 v16, 2, v4
	v_lshlrev_b32_e32 v17, 8, v4
	v_lshl_add_u32 v17, v15, 4, v17
	v_mad_i64_i32 v[28:29], s[10:11], v14, 48, s[4:5]
	v_mov_b32_e32 v19, v189
	v_mov_b32_e32 v18, v16
	v_lshl_add_u64 v[28:29], v[28:29], 0, v[18:19]
	v_mov_b64_e32 v[20:21], s[2:3]
	v_mad_i64_i32 v[30:31], s[10:11], v14, s80, v[20:21]
	v_mov_b32_e32 v18, v17
	v_lshl_add_u64 v[30:31], v[30:31], 0, v[18:19]
	v_ashrrev_i32_e32 v21, 31, v14
	v_mov_b32_e32 v20, v14
	v_lshlrev_b64 v[20:21], 10, v[20:21]
	v_lshl_add_u64 v[32:33], s[6:7], 0, v[20:21]
	v_lshl_add_u64 v[32:33], v[32:33], 0, v[18:19]
	s_mov_b64 s[12:13], 0x18000
	s_mov_b64 s[24:25], 0x600000
	s_mov_b64 s[26:27], 0x200000
	s_movk_i32 s22, 16
	global_load_dword v40, v[28:29], off
	global_load_dword v41, v[28:29], off offset:16
	global_load_dword v42, v[28:29], off offset:32
	global_load_dwordx4 v[44:47], v[30:31], off
	global_load_dwordx4 v[48:51], v[30:31], off offset:1024
	global_load_dwordx4 v[52:55], v[30:31], off offset:2048
	v_lshl_add_u64 v[28:29], v[28:29], 0, s[12:13]
	v_lshl_add_u64 v[30:31], v[30:31], 0, s[24:25]
.Lmg_loop:
	s_cmp_eq_u32 s22, 1
	s_cbranch_scc1 .Lmg_lastA
	global_load_dword v56, v[28:29], off
	global_load_dword v57, v[28:29], off offset:16
	global_load_dword v58, v[28:29], off offset:32
	global_load_dwordx4 v[60:63], v[30:31], off
	global_load_dwordx4 v[64:67], v[30:31], off offset:1024
	global_load_dwordx4 v[68:71], v[30:31], off offset:2048
	v_lshl_add_u64 v[28:29], v[28:29], 0, s[12:13]
	v_lshl_add_u64 v[30:31], v[30:31], 0, s[24:25]
	s_waitcnt vmcnt(6)
	v_max3_f32 v3, v40, v41, v42
	v_sub_f32_e32 v5, v40, v3
	v_sub_f32_e32 v6, v41, v3
	v_sub_f32_e32 v7, v42, v3
	v_mul_f32_e32 v5, 0x3fb8aa3b, v5
	v_mul_f32_e32 v6, 0x3fb8aa3b, v6
	v_mul_f32_e32 v7, 0x3fb8aa3b, v7
	v_exp_f32_e32 v5, v5
	v_exp_f32_e32 v6, v6
	v_exp_f32_e32 v7, v7
	s_nop 0
	v_add_f32_e32 v3, v5, v6
	v_add_f32_e32 v3, v7, v3
	v_div_scale_f32 v8, s[10:11], v3, v3, 1.0
	v_div_scale_f32 v10, vcc, 1.0, v3, 1.0
	v_rcp_f32_e32 v9, v8
	s_nop 0
	v_fma_f32 v11, -v8, v9, 1.0
	v_fmac_f32_e32 v9, v11, v9
	v_mul_f32_e32 v11, v10, v9
	v_fma_f32 v12, -v8, v11, v10
	v_fmac_f32_e32 v11, v12, v9
	v_fma_f32 v8, -v8, v11, v10
	v_div_fmas_f32 v8, v8, v9, v11
	v_div_fixup_f32 v8, v8, v3, 1.0
	v_mul_f32_e32 v5, v5, v8
	v_mul_f32_e32 v6, v6, v8
	v_mul_f32_e32 v7, v7, v8
	v_lshlrev_b32_e32 v9, 16, v44
	v_and_b32_e32 v10, 0xffff0000, v44
	v_lshlrev_b32_e32 v11, 16, v48
	v_and_b32_e32 v12, 0xffff0000, v48
	v_lshlrev_b32_e32 v13, 16, v52
	v_and_b32_e32 v22, 0xffff0000, v52
	v_mul_f32_e32 v9, v5, v9
	v_mul_f32_e32 v10, v5, v10
	v_fmac_f32_e32 v9, v6, v11
	v_fmac_f32_e32 v10, v6, v12
	v_fmac_f32_e32 v9, v7, v13
	v_fmac_f32_e32 v10, v7, v22
	v_cvt_pk_bf16_f32 v24, v9, v10
	v_lshlrev_b32_e32 v9, 16, v45
	v_and_b32_e32 v10, 0xffff0000, v45
	v_lshlrev_b32_e32 v11, 16, v49
	v_and_b32_e32 v12, 0xffff0000, v49
	v_lshlrev_b32_e32 v13, 16, v53
	v_and_b32_e32 v22, 0xffff0000, v53
	v_mul_f32_e32 v9, v5, v9
	v_mul_f32_e32 v10, v5, v10
	v_fmac_f32_e32 v9, v6, v11
	v_fmac_f32_e32 v10, v6, v12
	v_fmac_f32_e32 v9, v7, v13
	v_fmac_f32_e32 v10, v7, v22
	v_cvt_pk_bf16_f32 v25, v9, v10
	v_lshlrev_b32_e32 v9, 16, v46
	v_and_b32_e32 v10, 0xffff0000, v46
	v_lshlrev_b32_e32 v11, 16, v50
	v_and_b32_e32 v12, 0xffff0000, v50
	v_lshlrev_b32_e32 v13, 16, v54
	v_and_b32_e32 v22, 0xffff0000, v54
	v_mul_f32_e32 v9, v5, v9
	v_mul_f32_e32 v10, v5, v10
	v_fmac_f32_e32 v9, v6, v11
	v_fmac_f32_e32 v10, v6, v12
	v_fmac_f32_e32 v9, v7, v13
	v_fmac_f32_e32 v10, v7, v22
	v_cvt_pk_bf16_f32 v26, v9, v10
	v_lshlrev_b32_e32 v9, 16, v47
	v_and_b32_e32 v10, 0xffff0000, v47
	v_lshlrev_b32_e32 v11, 16, v51
	v_and_b32_e32 v12, 0xffff0000, v51
	v_lshlrev_b32_e32 v13, 16, v55
	v_and_b32_e32 v22, 0xffff0000, v55
	v_mul_f32_e32 v9, v5, v9
	v_mul_f32_e32 v10, v5, v10
	v_fmac_f32_e32 v9, v6, v11
	v_fmac_f32_e32 v10, v6, v12
	v_fmac_f32_e32 v9, v7, v13
	v_fmac_f32_e32 v10, v7, v22
	v_cvt_pk_bf16_f32 v27, v9, v10
	global_store_dwordx4 v[32:33], v[24:27], off
	v_lshl_add_u64 v[32:33], v[32:33], 0, s[26:27]
	s_sub_u32 s22, s22, 1
	s_cmp_eq_u32 s22, 1
	s_cbranch_scc1 .Lmg_lastB
	global_load_dword v40, v[28:29], off
	global_load_dword v41, v[28:29], off offset:16
	global_load_dword v42, v[28:29], off offset:32
	global_load_dwordx4 v[44:47], v[30:31], off
	global_load_dwordx4 v[48:51], v[30:31], off offset:1024
	global_load_dwordx4 v[52:55], v[30:31], off offset:2048
	v_lshl_add_u64 v[28:29], v[28:29], 0, s[12:13]
	v_lshl_add_u64 v[30:31], v[30:31], 0, s[24:25]
	s_waitcnt vmcnt(6)
; __device__ __forceinline__ float bflo(unsigned u) { return __uint_as_float(u << 16); }
; __device__ __forceinline__ float bfhi(unsigned u) { return __uint_as_float(u & 0xffff0000u); }
; __device__ __forceinline__ unsigned pk2(float lo, float hi) { f32x2 v = {lo, hi}; bf2_t b = __builtin_convertvector(v, bf2_t); return __builtin_bit_cast(unsigned, b); }
; __device__ __forceinline__ void attn_merge(int wv, const Args& a) {
;     ...
;     for (int i = gt; i < MTOK * 64; i += GT) {
;         const int tok = i >> 6, hh = (i >> 4) & 3, c = i & 15;
;         const float l0 = LSE[(size_t)tok * 12 + hh], l1 = LSE[(size_t)tok * 12 + 4 + hh], l2 = LSE[(size_t)tok * 12 + 8 + hh];
;         const float mxl = fmaxf(l0, fmaxf(l1, l2));
;         float a0 = __expf(l0 - mxl), a1 = __expf(l1 - mxl), a2 = __expf(l2 - mxl); const float inv = 1.f / (a0 + a1 + a2); a0 *= inv; a1 *= inv; a2 *= inv;
;         const u32x4 v0 = *(const u32x4*)(OG + (size_t)tok * ATW + hh * 128 + 8 * c), v1 = *(const u32x4*)(OG + (size_t)tok * ATW + (4 + hh) * 128 + 8 * c), v2 = *(const u32x4*)(OG + (size_t)tok * ATW + (8 + hh) * 128 + 8 * c);
;         u32x4 w;
;         w.x = pk2(a0 * bflo(v0.x) + a1 * bflo(v1.x) + a2 * bflo(v2.x), a0 * bfhi(v0.x) + a1 * bfhi(v1.x) + a2 * bfhi(v2.x));
;         w.y = pk2(a0 * bflo(v0.y) + a1 * bflo(v1.y) + a2 * bflo(v2.y), a0 * bfhi(v0.y) + a1 * bfhi(v1.y) + a2 * bfhi(v2.y));
;         w.z = pk2(a0 * bflo(v0.z) + a1 * bflo(v1.z) + a2 * bflo(v2.z), a0 * bfhi(v0.z) + a1 * bfhi(v1.z) + a2 * bfhi(v2.z));
;         w.w = pk2(a0 * bflo(v0.w) + a1 * bflo(v1.w) + a2 * bflo(v2.w), a0 * bfhi(v0.w) + a1 * bfhi(v1.w) + a2 * bfhi(v2.w));
;         *(u32x4*)(OB + (size_t)tok * 512 + hh * 128 + 8 * c) = w;
;     }
	v_max3_f32 v3, v56, v57, v58
	v_sub_f32_e32 v5, v56, v3
	v_sub_f32_e32 v6, v57, v3
	v_sub_f32_e32 v7, v58, v3
	v_mul_f32_e32 v5, 0x3fb8aa3b, v5
	v_mul_f32_e32 v6, 0x3fb8aa3b, v6
	v_mul_f32_e32 v7, 0x3fb8aa3b, v7
	v_exp_f32_e32 v5, v5
	v_exp_f32_e32 v6, v6
	v_exp_f32_e32 v7, v7
	s_nop 0
	v_add_f32_e32 v3, v5, v6
	v_add_f32_e32 v3, v7, v3
	v_div_scale_f32 v8, s[10:11], v3, v3, 1.0
	v_div_scale_f32 v10, vcc, 1.0, v3, 1.0
	v_rcp_f32_e32 v9, v8
	s_nop 0
	v_fma_f32 v11, -v8, v9, 1.0
	v_fmac_f32_e32 v9, v11, v9
	v_mul_f32_e32 v11, v10, v9
	v_fma_f32 v12, -v8, v11, v10
	v_fmac_f32_e32 v11, v12, v9
	v_fma_f32 v8, -v8, v11, v10
	v_div_fmas_f32 v8, v8, v9, v11
	v_div_fixup_f32 v8, v8, v3, 1.0
	v_mul_f32_e32 v5, v5, v8
	v_mul_f32_e32 v6, v6, v8
	v_mul_f32_e32 v7, v7, v8
	v_lshlrev_b32_e32 v9, 16, v60
	v_and_b32_e32 v10, 0xffff0000, v60
	v_lshlrev_b32_e32 v11, 16, v64
	v_and_b32_e32 v12, 0xffff0000, v64
	v_lshlrev_b32_e32 v13, 16, v68
	v_and_b32_e32 v22, 0xffff0000, v68
	v_mul_f32_e32 v9, v5, v9
	v_mul_f32_e32 v10, v5, v10
	v_fmac_f32_e32 v9, v6, v11
	v_fmac_f32_e32 v10, v6, v12
	v_fmac_f32_e32 v9, v7, v13
	v_fmac_f32_e32 v10, v7, v22
	v_cvt_pk_bf16_f32 v24, v9, v10
	v_lshlrev_b32_e32 v9, 16, v61
	v_and_b32_e32 v10, 0xffff0000, v61
	v_lshlrev_b32_e32 v11, 16, v65
	v_and_b32_e32 v12, 0xffff0000, v65
	v_lshlrev_b32_e32 v13, 16, v69
	v_and_b32_e32 v22, 0xffff0000, v69
	v_mul_f32_e32 v9, v5, v9
	v_mul_f32_e32 v10, v5, v10
	v_fmac_f32_e32 v9, v6, v11
	v_fmac_f32_e32 v10, v6, v12
	v_fmac_f32_e32 v9, v7, v13
	v_fmac_f32_e32 v10, v7, v22
	v_cvt_pk_bf16_f32 v25, v9, v10
	v_lshlrev_b32_e32 v9, 16, v62
	v_and_b32_e32 v10, 0xffff0000, v62
	v_lshlrev_b32_e32 v11, 16, v66
	v_and_b32_e32 v12, 0xffff0000, v66
	v_lshlrev_b32_e32 v13, 16, v70
	v_and_b32_e32 v22, 0xffff0000, v70
	v_mul_f32_e32 v9, v5, v9
	v_mul_f32_e32 v10, v5, v10
	v_fmac_f32_e32 v9, v6, v11
	v_fmac_f32_e32 v10, v6, v12
	v_fmac_f32_e32 v9, v7, v13
	v_fmac_f32_e32 v10, v7, v22
	v_cvt_pk_bf16_f32 v26, v9, v10
	v_lshlrev_b32_e32 v9, 16, v63
	v_and_b32_e32 v10, 0xffff0000, v63
	v_lshlrev_b32_e32 v11, 16, v67
	v_and_b32_e32 v12, 0xffff0000, v67
	v_lshlrev_b32_e32 v13, 16, v71
	v_and_b32_e32 v22, 0xffff0000, v71
	v_mul_f32_e32 v9, v5, v9
	v_mul_f32_e32 v10, v5, v10
	v_fmac_f32_e32 v9, v6, v11
	v_fmac_f32_e32 v10, v6, v12
	v_fmac_f32_e32 v9, v7, v13
	v_fmac_f32_e32 v10, v7, v22
	v_cvt_pk_bf16_f32 v27, v9, v10
	global_store_dwordx4 v[32:33], v[24:27], off
	v_lshl_add_u64 v[32:33], v[32:33], 0, s[26:27]
	s_sub_u32 s22, s22, 1
	s_branch .Lmg_loop
.Lmg_lastA:
	s_waitcnt vmcnt(0)
	v_max3_f32 v3, v40, v41, v42
	v_sub_f32_e32 v5, v40, v3
	v_sub_f32_e32 v6, v41, v3
	v_sub_f32_e32 v7, v42, v3
	v_mul_f32_e32 v5, 0x3fb8aa3b, v5
	v_mul_f32_e32 v6, 0x3fb8aa3b, v6
	v_mul_f32_e32 v7, 0x3fb8aa3b, v7
	v_exp_f32_e32 v5, v5
	v_exp_f32_e32 v6, v6
	v_exp_f32_e32 v7, v7
	s_nop 0
	v_add_f32_e32 v3, v5, v6
	v_add_f32_e32 v3, v7, v3
	v_div_scale_f32 v8, s[10:11], v3, v3, 1.0
	v_div_scale_f32 v10, vcc, 1.0, v3, 1.0
	v_rcp_f32_e32 v9, v8
	s_nop 0
	v_fma_f32 v11, -v8, v9, 1.0
	v_fmac_f32_e32 v9, v11, v9
	v_mul_f32_e32 v11, v10, v9
	v_fma_f32 v12, -v8, v11, v10
	v_fmac_f32_e32 v11, v12, v9
	v_fma_f32 v8, -v8, v11, v10
	v_div_fmas_f32 v8, v8, v9, v11
	v_div_fixup_f32 v8, v8, v3, 1.0
	v_mul_f32_e32 v5, v5, v8
	v_mul_f32_e32 v6, v6, v8
	v_mul_f32_e32 v7, v7, v8
	v_lshlrev_b32_e32 v9, 16, v44
	v_and_b32_e32 v10, 0xffff0000, v44
	v_lshlrev_b32_e32 v11, 16, v48
	v_and_b32_e32 v12, 0xffff0000, v48
	v_lshlrev_b32_e32 v13, 16, v52
	v_and_b32_e32 v22, 0xffff0000, v52
	v_mul_f32_e32 v9, v5, v9
	v_mul_f32_e32 v10, v5, v10
	v_fmac_f32_e32 v9, v6, v11
	v_fmac_f32_e32 v10, v6, v12
	v_fmac_f32_e32 v9, v7, v13
	v_fmac_f32_e32 v10, v7, v22
	v_cvt_pk_bf16_f32 v24, v9, v10
	v_lshlrev_b32_e32 v9, 16, v45
	v_and_b32_e32 v10, 0xffff0000, v45
	v_lshlrev_b32_e32 v11, 16, v49
	v_and_b32_e32 v12, 0xffff0000, v49
	v_lshlrev_b32_e32 v13, 16, v53
	v_and_b32_e32 v22, 0xffff0000, v53
	v_mul_f32_e32 v9, v5, v9
	v_mul_f32_e32 v10, v5, v10
	v_fmac_f32_e32 v9, v6, v11
	v_fmac_f32_e32 v10, v6, v12
	v_fmac_f32_e32 v9, v7, v13
	v_fmac_f32_e32 v10, v7, v22
	v_cvt_pk_bf16_f32 v25, v9, v10
	v_lshlrev_b32_e32 v9, 16, v46
	v_and_b32_e32 v10, 0xffff0000, v46
	v_lshlrev_b32_e32 v11, 16, v50
	v_and_b32_e32 v12, 0xffff0000, v50
	v_lshlrev_b32_e32 v13, 16, v54
	v_and_b32_e32 v22, 0xffff0000, v54
	v_mul_f32_e32 v9, v5, v9
	v_mul_f32_e32 v10, v5, v10
	v_fmac_f32_e32 v9, v6, v11
	v_fmac_f32_e32 v10, v6, v12
	v_fmac_f32_e32 v9, v7, v13
	v_fmac_f32_e32 v10, v7, v22
	v_cvt_pk_bf16_f32 v26, v9, v10
	v_lshlrev_b32_e32 v9, 16, v47
	v_and_b32_e32 v10, 0xffff0000, v47
	v_lshlrev_b32_e32 v11, 16, v51
	v_and_b32_e32 v12, 0xffff0000, v51
	v_lshlrev_b32_e32 v13, 16, v55
	v_and_b32_e32 v22, 0xffff0000, v55
	v_mul_f32_e32 v9, v5, v9
	v_mul_f32_e32 v10, v5, v10
	v_fmac_f32_e32 v9, v6, v11
	v_fmac_f32_e32 v10, v6, v12
	v_fmac_f32_e32 v9, v7, v13
	v_fmac_f32_e32 v10, v7, v22
	v_cvt_pk_bf16_f32 v27, v9, v10
	global_store_dwordx4 v[32:33], v[24:27], off
	v_lshl_add_u64 v[32:33], v[32:33], 0, s[26:27]
	s_branch .Lmg_done
; __device__ __forceinline__ float bflo(unsigned u) { return __uint_as_float(u << 16); }
; __device__ __forceinline__ float bfhi(unsigned u) { return __uint_as_float(u & 0xffff0000u); }
; __device__ __forceinline__ unsigned pk2(float lo, float hi) { f32x2 v = {lo, hi}; bf2_t b = __builtin_convertvector(v, bf2_t); return __builtin_bit_cast(unsigned, b); }
; __device__ __forceinline__ void attn_merge(int wv, const Args& a) {
;     ...
;     for (int i = gt; i < MTOK * 64; i += GT) {
;         const int tok = i >> 6, hh = (i >> 4) & 3, c = i & 15;
;         const float l0 = LSE[(size_t)tok * 12 + hh], l1 = LSE[(size_t)tok * 12 + 4 + hh], l2 = LSE[(size_t)tok * 12 + 8 + hh];
;         const float mxl = fmaxf(l0, fmaxf(l1, l2));
;         float a0 = __expf(l0 - mxl), a1 = __expf(l1 - mxl), a2 = __expf(l2 - mxl); const float inv = 1.f / (a0 + a1 + a2); a0 *= inv; a1 *= inv; a2 *= inv;
;         const u32x4 v0 = *(const u32x4*)(OG + (size_t)tok * ATW + hh * 128 + 8 * c), v1 = *(const u32x4*)(OG + (size_t)tok * ATW + (4 + hh) * 128 + 8 * c), v2 = *(const u32x4*)(OG + (size_t)tok * ATW + (8 + hh) * 128 + 8 * c);
;         u32x4 w;
;         w.x = pk2(a0 * bflo(v0.x) + a1 * bflo(v1.x) + a2 * bflo(v2.x), a0 * bfhi(v0.x) + a1 * bfhi(v1.x) + a2 * bfhi(v2.x));
;         w.y = pk2(a0 * bflo(v0.y) + a1 * bflo(v1.y) + a2 * bflo(v2.y), a0 * bfhi(v0.y) + a1 * bfhi(v1.y) + a2 * bfhi(v2.y));
;         w.z = pk2(a0 * bflo(v0.z) + a1 * bflo(v1.z) + a2 * bflo(v2.z), a0 * bfhi(v0.z) + a1 * bfhi(v1.z) + a2 * bfhi(v2.z));
;         w.w = pk2(a0 * bflo(v0.w) + a1 * bflo(v1.w) + a2 * bflo(v2.w), a0 * bfhi(v0.w) + a1 * bfhi(v1.w) + a2 * bfhi(v2.w));
;         *(u32x4*)(OB + (size_t)tok * 512 + hh * 128 + 8 * c) = w;
;     }
; __device__ __forceinline__ void xcd_barrier(const XcdBarrier& b, bool t0) {
;     asm volatile("s_waitcnt vmcnt(0)" ::: "memory");
;     __syncthreads();
;     if (t0) {
;         unsigned* bar = b.bar;
;         __builtin_amdgcn_s_waitcnt(0);
;         unsigned nloc = b.st[0], nx = b.st[1];
;         if (nloc == 0u) { xcd_barrier_complete(bar, b.x, nloc, nx); b.st[0] = nloc; b.st[1] = nx; }
.Lmg_lastB:
	s_waitcnt vmcnt(0)
	v_max3_f32 v3, v56, v57, v58
	v_sub_f32_e32 v5, v56, v3
	v_sub_f32_e32 v6, v57, v3
	v_sub_f32_e32 v7, v58, v3
	v_mul_f32_e32 v5, 0x3fb8aa3b, v5
	v_mul_f32_e32 v6, 0x3fb8aa3b, v6
	v_mul_f32_e32 v7, 0x3fb8aa3b, v7
	v_exp_f32_e32 v5, v5
	v_exp_f32_e32 v6, v6
	v_exp_f32_e32 v7, v7
	s_nop 0
	v_add_f32_e32 v3, v5, v6
	v_add_f32_e32 v3, v7, v3
	v_div_scale_f32 v8, s[10:11], v3, v3, 1.0
	v_div_scale_f32 v10, vcc, 1.0, v3, 1.0
	v_rcp_f32_e32 v9, v8
	s_nop 0
	v_fma_f32 v11, -v8, v9, 1.0
	v_fmac_f32_e32 v9, v11, v9
	v_mul_f32_e32 v11, v10, v9
	v_fma_f32 v12, -v8, v11, v10
	v_fmac_f32_e32 v11, v12, v9
	v_fma_f32 v8, -v8, v11, v10
	v_div_fmas_f32 v8, v8, v9, v11
	v_div_fixup_f32 v8, v8, v3, 1.0
	v_mul_f32_e32 v5, v5, v8
	v_mul_f32_e32 v6, v6, v8
	v_mul_f32_e32 v7, v7, v8
	v_lshlrev_b32_e32 v9, 16, v60
	v_and_b32_e32 v10, 0xffff0000, v60
	v_lshlrev_b32_e32 v11, 16, v64
	v_and_b32_e32 v12, 0xffff0000, v64
	v_lshlrev_b32_e32 v13, 16, v68
	v_and_b32_e32 v22, 0xffff0000, v68
	v_mul_f32_e32 v9, v5, v9
	v_mul_f32_e32 v10, v5, v10
	v_fmac_f32_e32 v9, v6, v11
	v_fmac_f32_e32 v10, v6, v12
	v_fmac_f32_e32 v9, v7, v13
	v_fmac_f32_e32 v10, v7, v22
	v_cvt_pk_bf16_f32 v24, v9, v10
	v_lshlrev_b32_e32 v9, 16, v61
	v_and_b32_e32 v10, 0xffff0000, v61
	v_lshlrev_b32_e32 v11, 16, v65
	v_and_b32_e32 v12, 0xffff0000, v65
	v_lshlrev_b32_e32 v13, 16, v69
	v_and_b32_e32 v22, 0xffff0000, v69
	v_mul_f32_e32 v9, v5, v9
	v_mul_f32_e32 v10, v5, v10
	v_fmac_f32_e32 v9, v6, v11
	v_fmac_f32_e32 v10, v6, v12
	v_fmac_f32_e32 v9, v7, v13
	v_fmac_f32_e32 v10, v7, v22
	v_cvt_pk_bf16_f32 v25, v9, v10
	v_lshlrev_b32_e32 v9, 16, v62
	v_and_b32_e32 v10, 0xffff0000, v62
	v_lshlrev_b32_e32 v11, 16, v66
	v_and_b32_e32 v12, 0xffff0000, v66
	v_lshlrev_b32_e32 v13, 16, v70
	v_and_b32_e32 v22, 0xffff0000, v70
	v_mul_f32_e32 v9, v5, v9
	v_mul_f32_e32 v10, v5, v10
	v_fmac_f32_e32 v9, v6, v11
	v_fmac_f32_e32 v10, v6, v12
	v_fmac_f32_e32 v9, v7, v13
	v_fmac_f32_e32 v10, v7, v22
	v_cvt_pk_bf16_f32 v26, v9, v10
	v_lshlrev_b32_e32 v9, 16, v63
	v_and_b32_e32 v10, 0xffff0000, v63
	v_lshlrev_b32_e32 v11, 16, v67
	v_and_b32_e32 v12, 0xffff0000, v67
	v_lshlrev_b32_e32 v13, 16, v71
	v_and_b32_e32 v22, 0xffff0000, v71
	v_mul_f32_e32 v9, v5, v9
	v_mul_f32_e32 v10, v5, v10
	v_fmac_f32_e32 v9, v6, v11
	v_fmac_f32_e32 v10, v6, v12
	v_fmac_f32_e32 v9, v7, v13
	v_fmac_f32_e32 v10, v7, v22
	v_cvt_pk_bf16_f32 v27, v9, v10
	global_store_dwordx4 v[32:33], v[24:27], off
	v_lshl_add_u64 v[32:33], v[32:33], 0, s[26:27]
.Lmg_done:
.LBB0_715:
	s_or_b64 exec, exec, s[0:1]
	v_readlane_b32 s2, v252, 4
	v_readlane_b32 s3, v252, 5
	s_getreg_b32 s4, hwreg(HW_REG_XCC_ID, 0, 4)
	v_mbcnt_lo_u32_b32 v0, -1, 0
	v_mbcnt_hi_u32_b32 v0, -1, v0
	v_readlane_b32 s0, v252, 1
	s_waitcnt vmcnt(0)
	s_barrier
	s_nop 0
	v_or_b32_e32 v0, s0, v0
	v_cmp_eq_u32_e32 vcc, 0, v0
	s_and_saveexec_b64 s[0:1], vcc
	s_xor_b64 s[0:1], exec, s[0:1]
	s_cbranch_execz .LBB0_768
	v_readlane_b32 s5, v253, 22
	s_load_dwordx2 s[2:3], s[2:3], 0x88
	s_waitcnt vmcnt(0) expcnt(0) lgkmcnt(0)
	v_mov_b32_e32 v0, s5
	ds_read_b32 v2, v0
	v_readlane_b32 s5, v253, 23
	s_and_b32 s18, s4, 15
	s_waitcnt lgkmcnt(0)
	v_cmp_ne_u32_e32 vcc, 0, v2
	v_mov_b32_e32 v0, s5
	ds_read_b32 v0, v0
	s_cbranch_vccnz .LBB0_731
	s_add_u32 s4, s2, 0x1000
	s_addc_u32 s5, s3, 0
	s_add_u32 s6, s2, 0x1100
	s_addc_u32 s7, s3, 0
	s_add_u32 s8, s2, 0x1200
	s_addc_u32 s9, s3, 0
	s_add_u32 s10, s2, 0x1300
	s_addc_u32 s11, s3, 0
	s_mov_b32 s19, 1
	s_branch .LBB0_719
